# grid barrier: L1/L2 invalidates issued at arrival (workgroup is parked until release) instead of after release; leader invalidates right after its L2 write-back
# baseline (speedup 1.0000x reference)
; __device__ __forceinline__ unsigned xb_add(unsigned* p, unsigned v) { return __hip_atomic_fetch_add(p, v, __ATOMIC_RELAXED, __HIP_MEMORY_SCOPE_AGENT); }
; __device__ __forceinline__ void xcd_barrier(const XcdBarrier& b) {
;     ...
;         __builtin_amdgcn_s_waitcnt(0);
;         unsigned nloc = b.st[0], nx = b.st[1];
;         if (nloc == 0u) { xcd_barrier_complete(bar, bx, nloc, nx); b.st[0] = nloc; b.st[1] = nx; }
;         const unsigned old = xb_add(&bar[XB_XSUB(bx)], 1u);
.LBB0_46:
	s_mov_b64 s[4:5], exec
	v_mbcnt_lo_u32_b32 v1, s4, 0
	v_mbcnt_hi_u32_b32 v1, s5, v1
	s_lshl_b32 s3, s3, 6
	s_mov_b32 s9, 0
	v_cmp_eq_u32_e32 vcc, 0, v1
	s_and_saveexec_b64 s[6:7], vcc
	s_cbranch_execz .LBB0_48
	s_add_i32 s8, s3, 0x500
	s_lshl_b64 s[8:9], s[8:9], 2
	v_readlane_b32 s10, v253, 8
	v_readlane_b32 s11, v253, 9
	s_add_u32 s8, s10, s8
	s_addc_u32 s9, s11, s9
	s_bcnt1_i32_b64 s4, s[4:5]
	v_mov_b32_e32 v3, 0
	v_mov_b32_e32 v4, s4
	buffer_inv sc1
	global_atomic_add v3, v3, v4, s[8:9] sc0

; __device__ __forceinline__ unsigned xb_add(unsigned* p, unsigned v) { return __hip_atomic_fetch_add(p, v, __ATOMIC_RELAXED, __HIP_MEMORY_SCOPE_AGENT); }
; __device__ __forceinline__ void xcd_barrier(const XcdBarrier& b) {
;     ...
;             __builtin_amdgcn_fence(__ATOMIC_RELEASE, "agent");
;             asm volatile("s_waitcnt vmcnt(0)" ::: "memory");
;             const unsigned og = xb_add(&bar[XB_TOP], 1u);
;     ...
;             __builtin_amdgcn_fence(__ATOMIC_ACQUIRE, "agent");
;             asm volatile("s_waitcnt vmcnt(0)" ::: "memory");
.LBB0_61:
	s_or_b64 exec, exec, s[6:7]
	s_waitcnt vmcnt(0)
	s_waitcnt vmcnt(0)
.LBB0_62:
	s_andn2_saveexec_b64 s[4:5], s[4:5]
	s_cbranch_execz .LBB0_82
	s_mov_b64 s[4:5], exec
	buffer_wbl2 sc1
	s_waitcnt lgkmcnt(0)
	s_waitcnt vmcnt(0)
	buffer_inv sc1
	v_mbcnt_lo_u32_b32 v1, s4, 0
	v_mbcnt_hi_u32_b32 v1, s5, v1
	v_cmp_eq_u32_e32 vcc, 0, v1
	s_and_saveexec_b64 s[6:7], vcc
	s_cbranch_execz .LBB0_65
	s_bcnt1_i32_b64 s4, s[4:5]
	v_mov_b32_e32 v2, 0x1dc83000
	v_mov_b32_e32 v3, s4
	global_atomic_add v2, v2, v3, s[80:81] offset:1024 sc0

; __device__ __forceinline__ unsigned xb_add(unsigned* p, unsigned v) { return __hip_atomic_fetch_add(p, v, __ATOMIC_RELAXED, __HIP_MEMORY_SCOPE_AGENT); }
; __device__ __forceinline__ void xcd_barrier(const XcdBarrier& b) {
;     ...
;             __builtin_amdgcn_fence(__ATOMIC_ACQUIRE, "agent");
;             xb_add(&bar[XB_XGEN(bx)], 1u);
.LBB0_79:
	s_or_b64 exec, exec, s[4:5]
	s_mov_b64 s[4:5], exec
	v_mbcnt_lo_u32_b32 v0, s4, 0
	v_mbcnt_hi_u32_b32 v0, s5, v0
	s_mov_b32 s9, 0
	v_cmp_eq_u32_e32 vcc, 0, v0
	s_waitcnt vmcnt(0)
	s_and_saveexec_b64 s[6:7], vcc
	s_cbranch_execz .LBB0_81
	s_add_i32 s8, s3, 0x900
	s_lshl_b64 s[8:9], s[8:9], 2
	v_readlane_b32 s10, v253, 8
	v_readlane_b32 s11, v253, 9
	s_add_u32 s8, s10, s8
	s_addc_u32 s9, s11, s9
	s_bcnt1_i32_b64 s3, s[4:5]
	v_mov_b32_e32 v0, 0
	v_mov_b32_e32 v1, s3
	global_atomic_add v0, v1, s[8:9]

; __device__ __forceinline__ unsigned xb_add(unsigned* p, unsigned v) { return __hip_atomic_fetch_add(p, v, __ATOMIC_RELAXED, __HIP_MEMORY_SCOPE_AGENT); }
; __device__ __forceinline__ void xcd_barrier(const XcdBarrier& b) {
;     ...
;         __builtin_amdgcn_s_waitcnt(0);
;         unsigned nloc = b.st[0], nx = b.st[1];
;         if (nloc == 0u) { xcd_barrier_complete(bar, bx, nloc, nx); b.st[0] = nloc; b.st[1] = nx; }
;         const unsigned old = xb_add(&bar[XB_XSUB(bx)], 1u);
.LBB0_133:
	s_mov_b64 s[4:5], exec
	v_mbcnt_lo_u32_b32 v0, s4, 0
	v_mbcnt_hi_u32_b32 v0, s5, v0
	s_lshl_b32 s22, s12, 6
	v_cmp_eq_u32_e32 vcc, 0, v0
	s_and_saveexec_b64 s[6:7], vcc
	s_cbranch_execz .LBB0_135
	s_add_i32 s78, s22, 0x500
	s_lshl_b64 s[8:9], s[78:79], 2
	v_readlane_b32 s12, v253, 8
	v_readlane_b32 s13, v253, 9
	s_add_u32 s8, s12, s8
	s_addc_u32 s9, s13, s9
	s_bcnt1_i32_b64 s4, s[4:5]
	v_mov_b32_e32 v4, s4
	buffer_inv sc1
	global_atomic_add v4, v1, v4, s[8:9] sc0

; __device__ __forceinline__ unsigned xb_add(unsigned* p, unsigned v) { return __hip_atomic_fetch_add(p, v, __ATOMIC_RELAXED, __HIP_MEMORY_SCOPE_AGENT); }
; __device__ __forceinline__ void xcd_barrier(const XcdBarrier& b) {
;     ...
;             __builtin_amdgcn_fence(__ATOMIC_RELEASE, "agent");
;             asm volatile("s_waitcnt vmcnt(0)" ::: "memory");
;             const unsigned og = xb_add(&bar[XB_TOP], 1u);
.LBB0_149:
	s_andn2_saveexec_b64 s[4:5], s[4:5]
	s_cbranch_execz .LBB0_169
	s_mov_b64 s[4:5], exec
	buffer_wbl2 sc1
	s_waitcnt lgkmcnt(0)
	s_waitcnt vmcnt(0)
	buffer_inv sc1
	v_mbcnt_lo_u32_b32 v0, s4, 0
	v_mbcnt_hi_u32_b32 v0, s5, v0
	v_cmp_eq_u32_e32 vcc, 0, v0
	s_and_saveexec_b64 s[6:7], vcc
	s_cbranch_execz .LBB0_152
	s_bcnt1_i32_b64 s4, s[4:5]
	v_mov_b32_e32 v3, s4
	v_readlane_b32 s4, v253, 59
	v_readlane_b32 s5, v253, 60
	s_nop 4
	global_atomic_add v3, v1, v3, s[4:5] sc0

; __device__ __forceinline__ unsigned xb_add(unsigned* p, unsigned v) { return __hip_atomic_fetch_add(p, v, __ATOMIC_RELAXED, __HIP_MEMORY_SCOPE_AGENT); }
; __device__ __forceinline__ void xcd_barrier(const XcdBarrier& b) {
;     ...
;             __builtin_amdgcn_fence(__ATOMIC_ACQUIRE, "agent");
;             xb_add(&bar[XB_XGEN(bx)], 1u);
.LBB0_166:
	s_or_b64 exec, exec, s[4:5]
	s_mov_b64 s[4:5], exec
	v_mbcnt_lo_u32_b32 v0, s4, 0
	v_mbcnt_hi_u32_b32 v0, s5, v0
	v_cmp_eq_u32_e32 vcc, 0, v0
	s_waitcnt vmcnt(0)
	s_and_saveexec_b64 s[6:7], vcc
	s_cbranch_execz .LBB0_168
	s_add_i32 s78, s22, 0x900
	s_lshl_b64 s[8:9], s[78:79], 2
	v_readlane_b32 s12, v253, 8
	v_readlane_b32 s13, v253, 9
	s_add_u32 s8, s12, s8
	s_addc_u32 s9, s13, s9
	s_bcnt1_i32_b64 s4, s[4:5]
	v_mov_b32_e32 v0, s4
	global_atomic_add v1, v0, s[8:9]

; __device__ __forceinline__ unsigned xb_add(unsigned* p, unsigned v) { return __hip_atomic_fetch_add(p, v, __ATOMIC_RELAXED, __HIP_MEMORY_SCOPE_AGENT); }
; __device__ __forceinline__ void xcd_barrier(const XcdBarrier& b) {
;     ...
;         __builtin_amdgcn_s_waitcnt(0);
;         unsigned nloc = b.st[0], nx = b.st[1];
;         if (nloc == 0u) { xcd_barrier_complete(bar, bx, nloc, nx); b.st[0] = nloc; b.st[1] = nx; }
;         const unsigned old = xb_add(&bar[XB_XSUB(bx)], 1u);
.LBB0_261:
	s_mov_b64 s[4:5], exec
	v_mbcnt_lo_u32_b32 v0, s4, 0
	v_mbcnt_hi_u32_b32 v0, s5, v0
	s_lshl_b32 s22, s10, 6
	v_cmp_eq_u32_e32 vcc, 0, v0
	s_and_saveexec_b64 s[6:7], vcc
	s_cbranch_execz .LBB0_263
	s_add_i32 s78, s22, 0x500
	s_lshl_b64 s[8:9], s[78:79], 2
	v_readlane_b32 s10, v253, 8
	v_readlane_b32 s11, v253, 9
	s_add_u32 s8, s10, s8
	s_addc_u32 s9, s11, s9
	s_bcnt1_i32_b64 s4, s[4:5]
	v_mov_b32_e32 v4, s4
	buffer_inv sc1
	global_atomic_add v4, v1, v4, s[8:9] sc0

; __device__ __forceinline__ unsigned xb_add(unsigned* p, unsigned v) { return __hip_atomic_fetch_add(p, v, __ATOMIC_RELAXED, __HIP_MEMORY_SCOPE_AGENT); }
; __device__ __forceinline__ void xcd_barrier(const XcdBarrier& b) {
;     ...
;             __builtin_amdgcn_fence(__ATOMIC_ACQUIRE, "agent");
;             xb_add(&bar[XB_XGEN(bx)], 1u);
.LBB0_294:
	s_or_b64 exec, exec, s[4:5]
	s_mov_b64 s[4:5], exec
	v_mbcnt_lo_u32_b32 v0, s4, 0
	v_mbcnt_hi_u32_b32 v0, s5, v0
	v_cmp_eq_u32_e32 vcc, 0, v0
	s_waitcnt vmcnt(0)
	s_and_saveexec_b64 s[6:7], vcc
	s_cbranch_execz .LBB0_296
	s_add_i32 s78, s22, 0x900
	s_lshl_b64 s[8:9], s[78:79], 2
	v_readlane_b32 s10, v253, 8
	v_readlane_b32 s11, v253, 9
	s_add_u32 s8, s10, s8
	s_addc_u32 s9, s11, s9
	s_bcnt1_i32_b64 s4, s[4:5]
	v_mov_b32_e32 v0, s4
	global_atomic_add v1, v0, s[8:9]

; __device__ __forceinline__ unsigned xb_add(unsigned* p, unsigned v) { return __hip_atomic_fetch_add(p, v, __ATOMIC_RELAXED, __HIP_MEMORY_SCOPE_AGENT); }
; __device__ __forceinline__ void xcd_barrier(const XcdBarrier& b) {
;     ...
;         __builtin_amdgcn_s_waitcnt(0);
;         unsigned nloc = b.st[0], nx = b.st[1];
;         if (nloc == 0u) { xcd_barrier_complete(bar, bx, nloc, nx); b.st[0] = nloc; b.st[1] = nx; }
;         const unsigned old = xb_add(&bar[XB_XSUB(bx)], 1u);
.LBB0_372:
	s_mov_b64 s[4:5], exec
	v_mbcnt_lo_u32_b32 v0, s4, 0
	v_mbcnt_hi_u32_b32 v0, s5, v0
	s_lshl_b32 s20, s10, 6
	v_cmp_eq_u32_e32 vcc, 0, v0
	s_and_saveexec_b64 s[6:7], vcc
	s_cbranch_execz .LBB0_374
	s_add_i32 s78, s20, 0x500
	s_lshl_b64 s[8:9], s[78:79], 2
	v_readlane_b32 s10, v253, 8
	v_readlane_b32 s11, v253, 9
	s_add_u32 s8, s10, s8
	s_addc_u32 s9, s11, s9
	s_bcnt1_i32_b64 s4, s[4:5]
	v_mov_b32_e32 v4, s4
	buffer_inv sc1
	global_atomic_add v4, v1, v4, s[8:9] sc0

; __device__ __forceinline__ unsigned xb_add(unsigned* p, unsigned v) { return __hip_atomic_fetch_add(p, v, __ATOMIC_RELAXED, __HIP_MEMORY_SCOPE_AGENT); }
; __device__ __forceinline__ void xcd_barrier(const XcdBarrier& b) {
;     ...
;             __builtin_amdgcn_fence(__ATOMIC_ACQUIRE, "agent");
;             xb_add(&bar[XB_XGEN(bx)], 1u);
.LBB0_405:
	s_or_b64 exec, exec, s[4:5]
	s_mov_b64 s[4:5], exec
	v_mbcnt_lo_u32_b32 v0, s4, 0
	v_mbcnt_hi_u32_b32 v0, s5, v0
	v_cmp_eq_u32_e32 vcc, 0, v0
	s_waitcnt vmcnt(0)
	s_and_saveexec_b64 s[6:7], vcc
	s_cbranch_execz .LBB0_407
	s_add_i32 s78, s20, 0x900
	s_lshl_b64 s[8:9], s[78:79], 2
	v_readlane_b32 s10, v253, 8
	v_readlane_b32 s11, v253, 9
	s_add_u32 s8, s10, s8
	s_addc_u32 s9, s11, s9
	s_bcnt1_i32_b64 s4, s[4:5]
	v_mov_b32_e32 v0, s4
	global_atomic_add v1, v0, s[8:9]

; __device__ __forceinline__ unsigned xb_add(unsigned* p, unsigned v) { return __hip_atomic_fetch_add(p, v, __ATOMIC_RELAXED, __HIP_MEMORY_SCOPE_AGENT); }
; __device__ __forceinline__ void xcd_barrier(const XcdBarrier& b) {
;     ...
;         __builtin_amdgcn_s_waitcnt(0);
;         unsigned nloc = b.st[0], nx = b.st[1];
;         if (nloc == 0u) { xcd_barrier_complete(bar, bx, nloc, nx); b.st[0] = nloc; b.st[1] = nx; }
;         const unsigned old = xb_add(&bar[XB_XSUB(bx)], 1u);
.LBB0_826:
	s_mov_b64 s[6:7], exec
	v_mbcnt_lo_u32_b32 v0, s6, 0
	v_mbcnt_hi_u32_b32 v0, s7, v0
	s_lshl_b32 s22, s12, 6
	v_cmp_eq_u32_e32 vcc, 0, v0
	s_and_saveexec_b64 s[8:9], vcc
	s_cbranch_execz .LBB0_828
	s_add_i32 s78, s22, 0x500
	s_lshl_b64 s[10:11], s[78:79], 2
	v_readlane_b32 s12, v253, 8
	v_readlane_b32 s13, v253, 9
	s_add_u32 s10, s12, s10
	s_addc_u32 s11, s13, s11
	s_bcnt1_i32_b64 s6, s[6:7]
	v_mov_b32_e32 v4, s6
	buffer_inv sc1
	global_atomic_add v4, v1, v4, s[10:11] sc0

; __device__ __forceinline__ unsigned xb_add(unsigned* p, unsigned v) { return __hip_atomic_fetch_add(p, v, __ATOMIC_RELAXED, __HIP_MEMORY_SCOPE_AGENT); }
; __device__ __forceinline__ void xcd_barrier(const XcdBarrier& b) {
;     ...
;             __builtin_amdgcn_fence(__ATOMIC_RELEASE, "agent");
;             asm volatile("s_waitcnt vmcnt(0)" ::: "memory");
;             const unsigned og = xb_add(&bar[XB_TOP], 1u);
;     ...
;             __builtin_amdgcn_fence(__ATOMIC_ACQUIRE, "agent");
;             asm volatile("s_waitcnt vmcnt(0)" ::: "memory");
.LBB0_841:
	s_or_b64 exec, exec, s[8:9]
	s_waitcnt vmcnt(0)
	s_waitcnt vmcnt(0)
.LBB0_842:
	s_andn2_saveexec_b64 s[6:7], s[6:7]
	s_cbranch_execz .LBB0_862
	s_mov_b64 s[6:7], exec
	buffer_wbl2 sc1
	s_waitcnt lgkmcnt(0)
	s_waitcnt vmcnt(0)
	buffer_inv sc1
	v_mbcnt_lo_u32_b32 v0, s6, 0
	v_mbcnt_hi_u32_b32 v0, s7, v0
	v_cmp_eq_u32_e32 vcc, 0, v0
	s_and_saveexec_b64 s[8:9], vcc
	s_cbranch_execz .LBB0_845
	s_bcnt1_i32_b64 s6, s[6:7]
	v_mov_b32_e32 v3, s6
	v_readlane_b32 s6, v253, 59
	v_readlane_b32 s7, v253, 60
	s_nop 4
	global_atomic_add v3, v1, v3, s[6:7] sc0

; __device__ __forceinline__ unsigned xb_add(unsigned* p, unsigned v) { return __hip_atomic_fetch_add(p, v, __ATOMIC_RELAXED, __HIP_MEMORY_SCOPE_AGENT); }
; __device__ __forceinline__ void xcd_barrier(const XcdBarrier& b) {
;     ...
;             __builtin_amdgcn_fence(__ATOMIC_ACQUIRE, "agent");
;             xb_add(&bar[XB_XGEN(bx)], 1u);
.LBB0_859:
	s_or_b64 exec, exec, s[6:7]
	s_mov_b64 s[6:7], exec
	v_mbcnt_lo_u32_b32 v0, s6, 0
	v_mbcnt_hi_u32_b32 v0, s7, v0
	v_cmp_eq_u32_e32 vcc, 0, v0
	s_waitcnt vmcnt(0)
	s_and_saveexec_b64 s[8:9], vcc
	s_cbranch_execz .LBB0_861
	s_add_i32 s78, s22, 0x900
	s_lshl_b64 s[10:11], s[78:79], 2
	v_readlane_b32 s12, v253, 8
	v_readlane_b32 s13, v253, 9
	s_add_u32 s10, s12, s10
	s_addc_u32 s11, s13, s11
	s_bcnt1_i32_b64 s6, s[6:7]
	v_mov_b32_e32 v0, s6
	global_atomic_add v1, v0, s[10:11]

; __device__ __forceinline__ unsigned xb_add(unsigned* p, unsigned v) { return __hip_atomic_fetch_add(p, v, __ATOMIC_RELAXED, __HIP_MEMORY_SCOPE_AGENT); }
; __device__ __forceinline__ void xcd_barrier(const XcdBarrier& b) {
;     ...
;             __builtin_amdgcn_fence(__ATOMIC_RELEASE, "agent");
;             asm volatile("s_waitcnt vmcnt(0)" ::: "memory");
;             const unsigned og = xb_add(&bar[XB_TOP], 1u);
.LBB0_1047:
	s_mov_b64 s[4:5], exec
	buffer_wbl2 sc1
	s_waitcnt lgkmcnt(0)
	s_waitcnt vmcnt(0)
	buffer_inv sc1
	v_mbcnt_lo_u32_b32 v0, s4, 0
	v_mbcnt_hi_u32_b32 v0, s5, v0
	v_cmp_eq_u32_e32 vcc, 0, v0
	s_and_saveexec_b64 s[6:7], vcc
	s_cbranch_execz .LBB0_1049
	s_bcnt1_i32_b64 s4, s[4:5]
	v_mov_b32_e32 v3, s4
	v_readlane_b32 s4, v253, 59
	v_readlane_b32 s5, v253, 60
	s_nop 4
	global_atomic_add v3, v1, v3, s[4:5] sc0

; __device__ __forceinline__ unsigned xb_add(unsigned* p, unsigned v) { return __hip_atomic_fetch_add(p, v, __ATOMIC_RELAXED, __HIP_MEMORY_SCOPE_AGENT); }
; __device__ __forceinline__ void xcd_barrier(const XcdBarrier& b) {
;     ...
;             __builtin_amdgcn_fence(__ATOMIC_ACQUIRE, "agent");
;             xb_add(&bar[XB_XGEN(bx)], 1u);
.LBB0_1063:
	s_or_b64 exec, exec, s[4:5]
	s_mov_b64 s[4:5], exec
	v_mbcnt_lo_u32_b32 v0, s4, 0
	v_mbcnt_hi_u32_b32 v0, s5, v0
	v_cmp_eq_u32_e32 vcc, 0, v0
	s_waitcnt vmcnt(0)
	s_and_saveexec_b64 s[6:7], vcc
	s_cbranch_execnz .LBB0_1064
	s_getpc_b64 s[98:99]
